# v40 + neighbourhood-attention QK waits trimmed to one counted lgkmcnt per K-fragment pair
# speedup vs baseline: 1.0022x; 1.0022x over previous
; __device__ __forceinline__ int crow(int r, int hi) { return (r & 3) + 8 * (r >> 2) + 4 * hi; }
;   p0 = f32x16{}; p1 = f32x16{};
; #pragma unroll
;   for (int d0 = DLO; d0 < DHI; ++d0) { int cb = (d0 * 16 + hi * 8) * 2;
;     bf16x8 b0 = *reinterpret_cast<const bf16x8*>((const char*)Ks + KSWZ(r32, cb));
;     bf16x8 b1 = *reinterpret_cast<const bf16x8*>((const char*)Ks + KSWZ(32 + r32, cb));
;     p0 = __builtin_amdgcn_mfma_f32_32x32x16_bf16(b0, qr[d0], p0, 0, 0, 0);
;     p1 = __builtin_amdgcn_mfma_f32_32x32x16_bf16(b1, qr[d0], p1, 0, 0, 0); }
; }
; __device__ __forceinline__ void na_item(const int g_wave, int b, int r, int hp, const bf16* __restrict__ proj, const float* __restrict__ rpb, bf16* __restrict__ cat, char* lds) {
;     ...
;     const float* bp = btab + (hl * 15 + (kr - r + 7)) * 31;
;     float tmax = NEG;
; #pragma unroll
;     for (int q = 0; q < 16; ++q) {
;       const int j0 = crow(q, hi), j1 = 32 + j0;
;       { const bool ok = (j0 >= cs) && (j0 < cs + 16); int dc = j0 - c + 15; dc = dc < 0 ? 0 : (dc > 30 ? 30 : dc);
;         const float bv = bp[dc]; p0[q] = ok ? fmaf(p0[q], C, bv) : NEG; tmax = fmaxf(tmax, p0[q]); }
;       { const bool ok = (j1 >= cs) && (j1 < cs + 16); int dc = j1 - c + 15; dc = dc < 0 ? 0 : (dc > 30 ? 30 : dc);
;         const float bv = bp[dc]; p1[q] = ok ? fmaf(p1[q], C, bv) : NEG; tmax = fmaxf(tmax, p1[q]); }
;     }
.Lna_active:
	s_barrier
	ds_read_b128 v[230:233], v218
	v_add_u32_e32 v0, v139, v137
	ds_read_b128 v[234:237], v0 offset:8192
	ds_read_b128 v[238:241], v219
	v_add_u32_e32 v0, v139, v141
	ds_read_b128 v[242:245], v0 offset:8192
	ds_read_b128 v[246:249], v220
	v_add_u32_e32 v0, v139, v143
	ds_read_b128 v[186:189], v0 offset:8192
	s_waitcnt lgkmcnt(4)
	v_mfma_f32_32x32x16_bf16 v[82:97], v[230:233], v[122:125], 0
	ds_read_b128 v[230:233], v221
	v_mfma_f32_32x32x16_bf16 v[66:81], v[234:237], v[122:125], 0
	v_add_u32_e32 v0, v139, v145
	ds_read_b128 v[234:237], v0 offset:8192
	s_waitcnt lgkmcnt(4)
	v_mfma_f32_32x32x16_bf16 v[82:97], v[238:241], v[98:101], v[82:97]
	ds_read_b128 v[238:241], v222
	v_mfma_f32_32x32x16_bf16 v[66:81], v[242:245], v[98:101], v[66:81]
	v_add_u32_e32 v0, v139, v149
	ds_read_b128 v[242:245], v0 offset:8192
	s_waitcnt lgkmcnt(4)
	v_mfma_f32_32x32x16_bf16 v[82:97], v[246:249], v[102:105], v[82:97]
	ds_read_b128 v[246:249], v223
	v_mfma_f32_32x32x16_bf16 v[66:81], v[186:189], v[102:105], v[66:81]
	v_add_u32_e32 v0, v139, v151
	ds_read_b128 v[186:189], v0 offset:8192
	s_waitcnt lgkmcnt(4)
	v_mfma_f32_32x32x16_bf16 v[82:97], v[230:233], v[106:109], v[82:97]
	ds_read_b128 v[230:233], v224
	v_mfma_f32_32x32x16_bf16 v[66:81], v[234:237], v[106:109], v[66:81]
	v_add_u32_e32 v0, v139, v153
	ds_read_b128 v[234:237], v0 offset:8192
	s_waitcnt lgkmcnt(4)
	v_mfma_f32_32x32x16_bf16 v[82:97], v[238:241], v[110:113], v[82:97]
	ds_read_b128 v[238:241], v225
	v_mfma_f32_32x32x16_bf16 v[66:81], v[242:245], v[110:113], v[66:81]
	v_add_u32_e32 v0, v139, v155
	ds_read_b128 v[242:245], v0 offset:8192
	s_waitcnt lgkmcnt(4)
	v_mfma_f32_32x32x16_bf16 v[82:97], v[246:249], v[114:117], v[82:97]
	v_mfma_f32_32x32x16_bf16 v[66:81], v[186:189], v[114:117], v[66:81]
	s_waitcnt lgkmcnt(2)
	v_mfma_f32_32x32x16_bf16 v[82:97], v[230:233], v[118:121], v[82:97]
	v_mfma_f32_32x32x16_bf16 v[66:81], v[234:237], v[118:121], v[66:81]
	s_waitcnt lgkmcnt(0)
	v_mfma_f32_32x32x16_bf16 v[82:97], v[238:241], v[126:129], v[82:97]
	v_mfma_f32_32x32x16_bf16 v[66:81], v[242:245], v[126:129], v[66:81]
	v_mov_b32_e32 v244, 0xf149f2ca
	v_add_u32_e32 v230, s43, v157
	ds_read_b32 v230, v230
	v_add_u32_e32 v231, s43, v159
	ds_read_b32 v231, v231
	v_add_u32_e32 v232, s43, v161
	ds_read_b32 v232, v232
	v_add_u32_e32 v233, s43, v164
	ds_read_b32 v233, v233
	v_add_u32_e32 v234, s43, v165
	ds_read_b32 v234, v234
	v_add_u32_e32 v235, s43, v166
	ds_read_b32 v235, v235
	v_add_u32_e32 v236, s43, v167
	ds_read_b32 v236, v236
	v_add_u32_e32 v237, s43, v168
	ds_read_b32 v237, v237
	v_add_u32_e32 v238, s43, v169
	ds_read_b32 v238, v238
	v_add_u32_e32 v239, s43, v170
	ds_read_b32 v239, v239
	v_add_u32_e32 v240, s43, v171
	ds_read_b32 v240, v240
	v_add_u32_e32 v241, s43, v172
	ds_read_b32 v241, v241
	v_add_u32_e32 v242, s43, v173
	ds_read_b32 v242, v242
	v_add_u32_e32 v243, s43, v174
	ds_read_b32 v243, v243
	s_waitcnt lgkmcnt(13)
	v_fmac_f32_e32 v230, 0x3e0293ee, v82
	v_cndmask_b32_e64 v229, v244, v230, s[26:27]
	v_add_u32_e32 v230, s43, v175
	ds_read_b32 v230, v230
	s_waitcnt lgkmcnt(13)
	v_fmac_f32_e32 v231, 0x3e0293ee, v66
	v_cndmask_b32_e64 v228, v244, v231, s[28:29]
	v_add_u32_e32 v231, s43, v176
	ds_read_b32 v231, v231
	s_waitcnt lgkmcnt(13)
	v_fmac_f32_e32 v232, 0x3e0293ee, v83
	v_cndmask_b32_e64 v82, v244, v232, s[30:31]
	v_add_u32_e32 v232, s43, v177
	ds_read_b32 v232, v232
	s_waitcnt lgkmcnt(13)
	v_fmac_f32_e32 v233, 0x3e0293ee, v67
	v_cndmask_b32_e64 v66, v244, v233, s[82:83]
	v_add_u32_e32 v233, s43, v190
	ds_read_b32 v233, v233
	s_waitcnt lgkmcnt(13)
	v_fmac_f32_e32 v234, 0x3e0293ee, v84
	v_cndmask_b32_e64 v83, v244, v234, s[84:85]
	v_add_u32_e32 v234, s43, v191
	ds_read_b32 v234, v234
	s_waitcnt lgkmcnt(13)
	v_fmac_f32_e32 v235, 0x3e0293ee, v68
	v_cndmask_b32_e64 v67, v244, v235, s[86:87]
	v_add_u32_e32 v235, s43, v192
	ds_read_b32 v235, v235
	s_waitcnt lgkmcnt(13)
	v_fmac_f32_e32 v236, 0x3e0293ee, v85
	v_cndmask_b32_e64 v84, v244, v236, s[88:89]
	v_add_u32_e32 v236, s43, v193
	ds_read_b32 v236, v236
	s_waitcnt lgkmcnt(13)
	v_fmac_f32_e32 v237, 0x3e0293ee, v69
	v_cndmask_b32_e64 v68, v244, v237, s[90:91]
	v_add_u32_e32 v237, s43, v194
	ds_read_b32 v237, v237
	s_waitcnt lgkmcnt(13)
	v_fmac_f32_e32 v238, 0x3e0293ee, v86
	v_cndmask_b32_e64 v85, v244, v238, s[92:93]
	v_add_u32_e32 v238, s43, v195
	ds_read_b32 v238, v238
	s_waitcnt lgkmcnt(13)
	v_fmac_f32_e32 v239, 0x3e0293ee, v70
	v_cndmask_b32_e64 v69, v244, v239, s[94:95]
	v_add_u32_e32 v239, s43, v196
	ds_read_b32 v239, v239
	s_waitcnt lgkmcnt(13)
	v_fmac_f32_e32 v240, 0x3e0293ee, v87
	v_cndmask_b32_e64 v86, v244, v240, s[96:97]
	v_add_u32_e32 v240, s43, v197
	ds_read_b32 v240, v240
	s_waitcnt lgkmcnt(13)
	v_fmac_f32_e32 v241, 0x3e0293ee, v71
	v_cndmask_b32_e64 v70, v244, v241, s[60:61]
	v_add_u32_e32 v241, s43, v207
	ds_read_b32 v241, v241
	s_waitcnt lgkmcnt(13)
	v_fmac_f32_e32 v242, 0x3e0293ee, v88
	v_cndmask_b32_e64 v87, v244, v242, s[38:39]
	v_add_u32_e32 v242, s43, v208
	ds_read_b32 v242, v242
	s_waitcnt lgkmcnt(13)
	v_fmac_f32_e32 v243, 0x3e0293ee, v72
	v_cndmask_b32_e64 v71, v244, v243, s[74:75]
	v_add_u32_e32 v243, s43, v209
	ds_read_b32 v243, v243
	s_waitcnt lgkmcnt(13)
	v_fmac_f32_e32 v230, 0x3e0293ee, v89
	v_cndmask_b32_e64 v88, v244, v230, s[36:37]
	v_add_u32_e32 v230, s43, v210
	ds_read_b32 v230, v230
	s_waitcnt lgkmcnt(13)
	v_fmac_f32_e32 v231, 0x3e0293ee, v73
	v_cndmask_b32_e64 v72, v244, v231, s[78:79]
	v_add_u32_e32 v231, s43, v211
	ds_read_b32 v231, v231
	s_waitcnt lgkmcnt(13)
	v_fmac_f32_e32 v232, 0x3e0293ee, v90
	v_cndmask_b32_e64 v89, v244, v232, s[4:5]
	v_add_u32_e32 v232, s43, v212
	ds_read_b32 v232, v232
	s_waitcnt lgkmcnt(13)
; __device__ __forceinline__ int crow(int r, int hi) { return (r & 3) + 8 * (r >> 2) + 4 * hi; }
; __device__ __forceinline__ void na_item(const int g_wave, int b, int r, int hp, const bf16* __restrict__ proj, const float* __restrict__ rpb, bf16* __restrict__ cat, char* lds) {
;     ...
;     const float* bp = btab + (hl * 15 + (kr - r + 7)) * 31;
;     float tmax = NEG;
; #pragma unroll
;     for (int q = 0; q < 16; ++q) {
;       const int j0 = crow(q, hi), j1 = 32 + j0;
;       { const bool ok = (j0 >= cs) && (j0 < cs + 16); int dc = j0 - c + 15; dc = dc < 0 ? 0 : (dc > 30 ? 30 : dc);
;         const float bv = bp[dc]; p0[q] = ok ? fmaf(p0[q], C, bv) : NEG; tmax = fmaxf(tmax, p0[q]); }
;       { const bool ok = (j1 >= cs) && (j1 < cs + 16); int dc = j1 - c + 15; dc = dc < 0 ? 0 : (dc > 30 ? 30 : dc);
;         const float bv = bp[dc]; p1[q] = ok ? fmaf(p1[q], C, bv) : NEG; tmax = fmaxf(tmax, p1[q]); }
;     }
;     { auto rr = __builtin_amdgcn_permlane32_swap(__float_as_uint(tmax), __float_as_uint(tmax), false, false);
;       tmax = fmaxf(__uint_as_float(rr[0]), __uint_as_float(rr[1])); }
;     const float mn = fmaxf(m_reg, tmax); const float alpha = __builtin_amdgcn_exp2f(m_reg - mn); m_reg = mn;
;     float ps = 0.f;
; #pragma unroll
;     for (int q = 0; q < 16; ++q) { p0[q] = __builtin_amdgcn_exp2f(p0[q] - mn); p1[q] = __builtin_amdgcn_exp2f(p1[q] - mn); ps += p0[q] + p1[q]; }
;     { auto rr = __builtin_amdgcn_permlane32_swap(__float_as_uint(ps), __float_as_uint(ps), false, false);
;       ps = __uint_as_float(rr[0]) + __uint_as_float(rr[1]); }
;     l_reg = l_reg * alpha + ps;
;     bf16x8 pa0, pa1, pa2, pa3;
;     PK4(p0, 0, pa0); PK4(p0, 8, pa1); PK4(p1, 0, pa2); PK4(p1, 8, pa3);
;     if (hi == 0) al_l[r32] = alpha; asm volatile("s_waitcnt lgkmcnt(0)" ::: "memory");
	v_fmac_f32_e32 v233, 0x3e0293ee, v74
	v_cndmask_b32_e64 v73, v244, v233, s[14:15]
	v_add_u32_e32 v233, s43, v213
	ds_read_b32 v233, v233
	s_waitcnt lgkmcnt(13)
	v_fmac_f32_e32 v234, 0x3e0293ee, v91
	v_cndmask_b32_e64 v90, v244, v234, s[70:71]
	s_waitcnt lgkmcnt(12)
	v_fmac_f32_e32 v235, 0x3e0293ee, v75
	v_cndmask_b32_e64 v74, v244, v235, s[76:77]
	s_waitcnt lgkmcnt(11)
	v_fmac_f32_e32 v236, 0x3e0293ee, v92
	v_cndmask_b32_e64 v91, v244, v236, s[12:13]
	s_waitcnt lgkmcnt(10)
	v_fmac_f32_e32 v237, 0x3e0293ee, v76
	v_cndmask_b32_e64 v75, v244, v237, s[48:49]
	s_waitcnt lgkmcnt(9)
	v_fmac_f32_e32 v238, 0x3e0293ee, v93
	v_cndmask_b32_e64 v92, v244, v238, s[46:47]
	s_waitcnt lgkmcnt(8)
	v_fmac_f32_e32 v239, 0x3e0293ee, v77
	v_cndmask_b32_e64 v76, v244, v239, s[2:3]
	s_waitcnt lgkmcnt(7)
	v_fmac_f32_e32 v240, 0x3e0293ee, v94
	v_cndmask_b32_e64 v93, v244, v240, s[50:51]
	s_waitcnt lgkmcnt(6)
	v_fmac_f32_e32 v241, 0x3e0293ee, v78
	v_cndmask_b32_e64 v77, v244, v241, s[56:57]
	s_waitcnt lgkmcnt(5)
	v_fmac_f32_e32 v242, 0x3e0293ee, v95
	v_cndmask_b32_e64 v94, v244, v242, s[58:59]
	s_waitcnt lgkmcnt(4)
	v_fmac_f32_e32 v243, 0x3e0293ee, v79
	v_cndmask_b32_e64 v78, v244, v243, s[44:45]
	s_waitcnt lgkmcnt(3)
	v_fmac_f32_e32 v230, 0x3e0293ee, v96
	v_cndmask_b32_e64 v95, v244, v230, s[80:81]
	s_waitcnt lgkmcnt(2)
	v_fmac_f32_e32 v231, 0x3e0293ee, v80
	v_cndmask_b32_e64 v79, v244, v231, s[34:35]
	s_waitcnt lgkmcnt(1)
	v_fmac_f32_e32 v232, 0x3e0293ee, v97
	v_cndmask_b32_e64 v96, v244, v232, s[72:73]
	s_waitcnt lgkmcnt(0)
	v_fmac_f32_e32 v233, 0x3e0293ee, v81
	v_cndmask_b32_e64 v80, v244, v233, s[8:9]
	s_mov_b32 s33, 0xf149f2ca
	v_max3_f32 v0, v229, s33, v228
	v_max3_f32 v0, v0, v82, v66
	v_max3_f32 v0, v0, v83, v67
	v_max3_f32 v0, v0, v84, v68
	v_max3_f32 v0, v0, v85, v69
	v_max3_f32 v0, v0, v86, v70
	v_max3_f32 v0, v0, v87, v71
	v_max3_f32 v0, v0, v88, v72
	v_max3_f32 v0, v0, v89, v73
	v_max3_f32 v0, v0, v90, v74
	v_max3_f32 v0, v0, v91, v75
	v_max3_f32 v0, v0, v92, v76
	v_max3_f32 v0, v0, v93, v77
	v_max3_f32 v0, v0, v94, v78
	v_max3_f32 v0, v0, v95, v79
	v_max3_f32 v0, v0, v96, v80
	v_mov_b32_e32 v81, v0
	s_nop 1
	v_permlane32_swap_b32_e32 v0, v81
	v_max3_f32 v0, v227, v0, v81
	v_sub_f32_e32 v81, v229, v0
	v_sub_f32_e32 v97, v228, v0
	v_exp_f32_e32 v81, v81
	v_exp_f32_e32 v97, v97
	v_sub_f32_e32 v82, v82, v0
	v_sub_f32_e32 v66, v66, v0
	v_exp_f32_e32 v186, v82
	v_exp_f32_e32 v187, v66
	v_sub_f32_e32 v83, v83, v0
	v_sub_f32_e32 v67, v67, v0
	v_sub_f32_e32 v66, v227, v0
	v_exp_f32_e32 v189, v83
	v_exp_f32_e32 v227, v67
	v_sub_f32_e32 v67, v84, v0
	v_sub_f32_e32 v68, v68, v0
	v_exp_f32_e32 v67, v67
	v_exp_f32_e32 v228, v68
	v_add_f32_e32 v82, v81, v97
	v_add_f32_e32 v82, 0, v82
	v_add_f32_e32 v188, v186, v187
	v_add_f32_e32 v68, v188, v82
	v_add_f32_e32 v82, v189, v227
	v_sub_f32_e32 v83, v85, v0
	v_sub_f32_e32 v69, v69, v0
	v_add_f32_e32 v68, v82, v68
	v_add_f32_e32 v82, v67, v228
	v_exp_f32_e32 v85, v83
	v_exp_f32_e32 v188, v69
	v_sub_f32_e32 v69, v86, v0
	v_sub_f32_e32 v70, v70, v0
	v_exp_f32_e32 v69, v69
	v_exp_f32_e32 v86, v70
	v_add_f32_e32 v68, v82, v68
	v_sub_f32_e32 v82, v87, v0
	v_sub_f32_e32 v71, v71, v0
	v_exp_f32_e32 v87, v82
	v_exp_f32_e32 v229, v71
	v_sub_f32_e32 v71, v88, v0
	v_sub_f32_e32 v72, v72, v0
	v_exp_f32_e32 v71, v71
	v_exp_f32_e32 v88, v72
	v_sub_f32_e32 v72, v89, v0
	v_sub_f32_e32 v73, v73, v0
	v_add_f32_e32 v70, v85, v188
	v_exp_f32_e32 v72, v72
	v_exp_f32_e32 v89, v73
	v_sub_f32_e32 v73, v90, v0
	v_sub_f32_e32 v74, v74, v0
	v_add_f32_e32 v68, v70, v68
	v_add_f32_e32 v70, v69, v86
	v_exp_f32_e32 v73, v73
	v_exp_f32_e32 v90, v74
	v_sub_f32_e32 v74, v91, v0
	v_sub_f32_e32 v75, v75, v0
	v_add_f32_e32 v68, v70, v68
	v_add_f32_e32 v70, v87, v229
	v_exp_f32_e32 v74, v74
	v_exp_f32_e32 v91, v75
	v_sub_f32_e32 v75, v92, v0
	v_sub_f32_e32 v76, v76, v0
	v_add_f32_e32 v68, v70, v68
	v_add_f32_e32 v70, v71, v88
	v_exp_f32_e32 v75, v75
	v_exp_f32_e32 v92, v76
	v_sub_f32_e32 v76, v93, v0
	v_sub_f32_e32 v77, v77, v0
	v_add_f32_e32 v68, v70, v68
	v_add_f32_e32 v70, v72, v89
	v_exp_f32_e32 v76, v76
	v_exp_f32_e32 v93, v77
	v_sub_f32_e32 v77, v94, v0
	v_sub_f32_e32 v78, v78, v0
	v_add_f32_e32 v68, v70, v68
	v_add_f32_e32 v70, v73, v90
	v_exp_f32_e32 v77, v77
	v_exp_f32_e32 v94, v78
	v_sub_f32_e32 v78, v95, v0
	v_sub_f32_e32 v79, v79, v0
	v_add_f32_e32 v68, v70, v68
	v_add_f32_e32 v70, v74, v91
	v_exp_f32_e32 v78, v78
	v_exp_f32_e32 v95, v79
	v_sub_f32_e32 v79, v96, v0
	v_sub_f32_e32 v80, v80, v0
	v_add_f32_e32 v68, v70, v68
	v_add_f32_e32 v70, v75, v92
	v_exp_f32_e32 v79, v79
	v_exp_f32_e32 v96, v80
	v_add_f32_e32 v68, v70, v68
	v_add_f32_e32 v70, v76, v93
	v_add_f32_e32 v68, v70, v68
	v_add_f32_e32 v70, v77, v94
	v_add_f32_e32 v68, v70, v68
	v_add_f32_e32 v70, v78, v95
	v_add_f32_e32 v68, v70, v68
	v_add_f32_e32 v70, v79, v96
	v_exp_f32_e32 v82, v66
	v_add_f32_e32 v83, v70, v68
	v_mov_b32_e32 v84, v83
	v_cvt_pk_bf16_f32 v66, v81, v186
	v_cvt_pk_bf16_f32 v67, v189, v67
	v_cvt_pk_bf16_f32 v68, v85, v69
	v_cvt_pk_bf16_f32 v69, v87, v71
	v_cvt_pk_bf16_f32 v70, v72, v73
	v_cvt_pk_bf16_f32 v71, v74, v75
	v_cvt_pk_bf16_f32 v72, v76, v77
	v_cvt_pk_bf16_f32 v73, v78, v79
	v_cvt_pk_bf16_f32 v74, v97, v187
	v_cvt_pk_bf16_f32 v75, v227, v228
	v_cvt_pk_bf16_f32 v76, v188, v86
	v_cvt_pk_bf16_f32 v77, v229, v88
	v_cvt_pk_bf16_f32 v78, v89, v90
	v_cvt_pk_bf16_f32 v79, v91, v92
	v_cvt_pk_bf16_f32 v80, v93, v94
	v_cvt_pk_bf16_f32 v81, v95, v96
	s_nop 1
	v_permlane32_swap_b32_e32 v83, v84
	v_permlane32_swap_b32_e32 v66, v68
	v_permlane32_swap_b32_e32 v67, v69
	v_permlane32_swap_b32_e32 v70, v72
	v_permlane32_swap_b32_e32 v71, v73
	v_permlane32_swap_b32_e32 v74, v76
	v_permlane32_swap_b32_e32 v75, v77
	v_permlane32_swap_b32_e32 v78, v80
	v_permlane32_swap_b32_e32 v79, v81
	s_and_saveexec_b64 s[68:69], s[6:7]
	ds_write_b32 v147, v82 offset:128
	s_or_b64 exec, exec, s[68:69]
	v_add_f32_e32 v186, v83, v84
	s_waitcnt lgkmcnt(0)
; #define SBAR() __builtin_amdgcn_sched_barrier(0)
; __device__ __forceinline__ int crow(int r, int hi) { return (r & 3) + 8 * (r >> 2) + 4 * hi; }
; template <int D0> __device__ __forceinline__ void pv_one(f32x16& od, int vb, bf16x8 pa0, bf16x8 pa1, bf16x8 pa2, bf16x8 pa3) {
;   const s16x4 l0 = tr_read<v_rd_off(D0, 0, 0)>(vb), h0 = tr_read<v_rd_off(D0, 0, 1)>(vb), l1 = tr_read<v_rd_off(D0, 1, 0)>(vb), h1 = tr_read<v_rd_off(D0, 1, 1)>(vb);
;   const s16x4 l2 = tr_read<v_rd_off(D0, 2, 0)>(vb), h2 = tr_read<v_rd_off(D0, 2, 1)>(vb), l3 = tr_read<v_rd_off(D0, 3, 0)>(vb), h3 = tr_read<v_rd_off(D0, 3, 1)>(vb);
;   asm volatile("s_waitcnt lgkmcnt(0)" ::: "memory"); SBAR();
;     ...
;   od = __builtin_amdgcn_mfma_f32_32x32x16_bf16(pa0, PK(l0, h0), od, 0, 0, 0);
;   od = __builtin_amdgcn_mfma_f32_32x32x16_bf16(pa1, PK(l1, h1), od, 0, 0, 0);
;   od = __builtin_amdgcn_mfma_f32_32x32x16_bf16(pa2, PK(l2, h2), od, 0, 0, 0);
;   od = __builtin_amdgcn_mfma_f32_32x32x16_bf16(pa3, PK(l3, h3), od, 0, 0, 0);
;     ...
; }
; __device__ __forceinline__ void na_item(const int g_wave, int b, int r, int hp, const bf16* __restrict__ proj, const float* __restrict__ rpb, bf16* __restrict__ cat, char* lds) {
;     ...
;     if (hi == 0) al_l[r32] = alpha; asm volatile("s_waitcnt lgkmcnt(0)" ::: "memory");
; #pragma unroll
;     for (int d = 0; d < 4; ++d)
; #pragma unroll
;       for (int q = 0; q < 16; ++q) o[d][q] *= al_l[crow(q, hi)];
;     pv_d0(o, vb, pa0, pa1, pa2, pa3);
	v_add_u32_e32 v94, s42, v135
	v_fmac_f32_e32 v186, v226, v82
	ds_read_b128 v[82:85], v94 offset:128
	ds_read_b128 v[86:89], v94 offset:160
	ds_read_b128 v[90:93], v94 offset:192
	ds_read_b128 v[94:97], v94 offset:224
	s_waitcnt lgkmcnt(3)
	v_pk_mul_f32 v[50:51], v[50:51], v[82:83]
	v_pk_mul_f32 v[34:35], v[34:35], v[82:83]
	v_pk_mul_f32 v[18:19], v[18:19], v[82:83]
	v_pk_mul_f32 v[2:3], v[2:3], v[82:83]
	ds_read_b64_tr_b16 v[82:83], v133 offset:0
	v_pk_mul_f32 v[52:53], v[52:53], v[84:85]
	v_pk_mul_f32 v[36:37], v[36:37], v[84:85]
	v_pk_mul_f32 v[20:21], v[20:21], v[84:85]
	v_pk_mul_f32 v[4:5], v[4:5], v[84:85]
	ds_read_b64_tr_b16 v[84:85], v133 offset:0x800
	s_waitcnt lgkmcnt(2)
	v_pk_mul_f32 v[54:55], v[54:55], v[86:87]
	v_pk_mul_f32 v[38:39], v[38:39], v[86:87]
	v_pk_mul_f32 v[22:23], v[22:23], v[86:87]
	v_pk_mul_f32 v[6:7], v[6:7], v[86:87]
	ds_read_b64_tr_b16 v[86:87], v133 offset:0x1000
	v_pk_mul_f32 v[56:57], v[56:57], v[88:89]
	v_pk_mul_f32 v[40:41], v[40:41], v[88:89]
	v_pk_mul_f32 v[24:25], v[24:25], v[88:89]
	v_pk_mul_f32 v[8:9], v[8:9], v[88:89]
	ds_read_b64_tr_b16 v[88:89], v133 offset:0x1800
	s_waitcnt lgkmcnt(1)
	v_pk_mul_f32 v[58:59], v[58:59], v[90:91]
	v_pk_mul_f32 v[42:43], v[42:43], v[90:91]
	v_pk_mul_f32 v[26:27], v[26:27], v[90:91]
	v_pk_mul_f32 v[10:11], v[10:11], v[90:91]
	ds_read_b64_tr_b16 v[90:91], v133 offset:0x2000
	v_pk_mul_f32 v[60:61], v[60:61], v[92:93]
	v_pk_mul_f32 v[44:45], v[44:45], v[92:93]
	v_pk_mul_f32 v[28:29], v[28:29], v[92:93]
	v_pk_mul_f32 v[12:13], v[12:13], v[92:93]
	ds_read_b64_tr_b16 v[92:93], v133 offset:0x2800
	s_waitcnt lgkmcnt(0)
	v_pk_mul_f32 v[62:63], v[62:63], v[94:95]
	v_pk_mul_f32 v[46:47], v[46:47], v[94:95]
	v_pk_mul_f32 v[30:31], v[30:31], v[94:95]
	v_pk_mul_f32 v[14:15], v[14:15], v[94:95]
	ds_read_b64_tr_b16 v[94:95], v133 offset:0x3000
	v_pk_mul_f32 v[64:65], v[64:65], v[96:97]
	v_pk_mul_f32 v[48:49], v[48:49], v[96:97]
	v_pk_mul_f32 v[32:33], v[32:33], v[96:97]
	v_pk_mul_f32 v[16:17], v[16:17], v[96:97]
	ds_read_b64_tr_b16 v[96:97], v133 offset:0x3800
	s_waitcnt lgkmcnt(0)
	v_mfma_f32_32x32x16_bf16 v[50:65], v[66:69], v[82:85], v[50:65]
	ds_read_b64_tr_b16 v[82:83], v133 offset:0x200
	ds_read_b64_tr_b16 v[84:85], v133 offset:0xa00
	v_mfma_f32_32x32x16_bf16 v[50:65], v[70:73], v[86:89], v[50:65]
	ds_read_b64_tr_b16 v[86:87], v133 offset:0x1200
	ds_read_b64_tr_b16 v[88:89], v133 offset:0x1a00
	v_mfma_f32_32x32x16_bf16 v[50:65], v[74:77], v[90:93], v[50:65]
	ds_read_b64_tr_b16 v[90:91], v133 offset:0x2200
	ds_read_b64_tr_b16 v[92:93], v133 offset:0x2a00
	v_mfma_f32_32x32x16_bf16 v[50:65], v[78:81], v[94:97], v[50:65]
	ds_read_b64_tr_b16 v[94:95], v133 offset:0x3200
	ds_read_b64_tr_b16 v[96:97], v133 offset:0x3a00
	s_waitcnt lgkmcnt(0)
	v_mfma_f32_32x32x16_bf16 v[34:49], v[66:69], v[82:85], v[34:49]
	ds_read_b64_tr_b16 v[82:83], v133 offset:0x400
	ds_read_b64_tr_b16 v[84:85], v133 offset:0xc00
	v_mfma_f32_32x32x16_bf16 v[34:49], v[70:73], v[86:89], v[34:49]
	ds_read_b64_tr_b16 v[86:87], v133 offset:0x1400
	ds_read_b64_tr_b16 v[88:89], v133 offset:0x1c00
	v_mfma_f32_32x32x16_bf16 v[34:49], v[74:77], v[90:93], v[34:49]
	ds_read_b64_tr_b16 v[90:91], v133 offset:0x2400
	ds_read_b64_tr_b16 v[92:93], v133 offset:0x2c00
	v_mfma_f32_32x32x16_bf16 v[34:49], v[78:81], v[94:97], v[34:49]
	ds_read_b64_tr_b16 v[94:95], v133 offset:0x3400
	ds_read_b64_tr_b16 v[96:97], v133 offset:0x3c00
	s_waitcnt lgkmcnt(0)
	v_mfma_f32_32x32x16_bf16 v[18:33], v[66:69], v[82:85], v[18:33]
	ds_read_b64_tr_b16 v[82:83], v133 offset:0x600
	ds_read_b64_tr_b16 v[84:85], v133 offset:0xe00
	v_mfma_f32_32x32x16_bf16 v[18:33], v[70:73], v[86:89], v[18:33]
	ds_read_b64_tr_b16 v[86:87], v133 offset:0x1600
	ds_read_b64_tr_b16 v[88:89], v133 offset:0x1e00
	v_mfma_f32_32x32x16_bf16 v[18:33], v[74:77], v[90:93], v[18:33]
	ds_read_b64_tr_b16 v[90:91], v133 offset:0x2600
	ds_read_b64_tr_b16 v[92:93], v133 offset:0x2e00
	v_mfma_f32_32x32x16_bf16 v[18:33], v[78:81], v[94:97], v[18:33]
	ds_read_b64_tr_b16 v[94:95], v133 offset:0x3600
	ds_read_b64_tr_b16 v[96:97], v133 offset:0x3e00
	s_waitcnt lgkmcnt(0)
	v_mfma_f32_32x32x16_bf16 v[2:17], v[66:69], v[82:85], v[2:17]
	v_mov_b32_e32 v226, v186
	v_mfma_f32_32x32x16_bf16 v[2:17], v[70:73], v[86:89], v[2:17]
	v_mfma_f32_32x32x16_bf16 v[2:17], v[74:77], v[90:93], v[2:17]
	v_mfma_f32_32x32x16_bf16 v[2:17], v[78:81], v[94:97], v[2:17]
	s_addk_i32 s43, 0x7c
	s_cmpk_eq_i32 s43, 0x3e0
	v_lshl_add_u64 v[162:163], v[162:163], 0, s[54:55]
	s_cbranch_scc0 .LBB0_1145
	s_branch .LBB0_1146
